# nt hints extended to the other single-use streams: P5 x1 loads, P8 loads and final stores, P4/P7 residual-epilogue loads (on top of P0 nt loads)
# speedup vs baseline: 1.0190x; 1.0004x over previous
.LBB0_567:
	v_lshl_add_u32 v152, s48, 8, v142
	v_lshl_or_b32 v154, s81, 8, v144
	v_ashrrev_i32_e32 v153, 31, v152
	v_ashrrev_i32_e32 v155, 31, v154
	v_lshlrev_b64 v[140:141], 11, v[152:153]
	v_lshl_add_u64 v[140:141], v[140:141], 0, v[154:155]
	v_lshlrev_b64 v[140:141], 2, v[140:141]
	s_andn2_b64 vcc, exec, s[4:5]
	s_mov_b64 s[4:5], -1
	v_mov_b32_e32 v226, v140
	v_add_u32_e32 v227, 0x20000, v140
	v_add_u32_e32 v228, 0x40000, v140
	v_add_u32_e32 v229, 0x60000, v140
	v_add_u32_e32 v230, 0x100000, v140
	v_add_u32_e32 v231, 0x120000, v140
	v_add_u32_e32 v232, 0x140000, v140
	v_add_u32_e32 v233, 0x160000, v140
	global_load_dwordx4 v[160:163], v226, s[36:37] offset:0 nt
	global_load_dwordx4 v[164:167], v226, s[36:37] offset:64 nt
	global_load_dwordx4 v[168:171], v226, s[36:37] offset:512 nt
	global_load_dwordx4 v[172:175], v226, s[36:37] offset:576 nt
	global_load_dwordx4 v[176:179], v227, s[36:37] offset:0 nt
	global_load_dwordx4 v[180:183], v227, s[36:37] offset:64 nt
	global_load_dwordx4 v[184:187], v227, s[36:37] offset:512 nt
	global_load_dwordx4 v[188:191], v227, s[36:37] offset:576 nt
	global_load_dwordx4 v[192:195], v228, s[36:37] offset:0 nt
	global_load_dwordx4 v[196:199], v228, s[36:37] offset:64 nt
	global_load_dwordx4 v[200:203], v228, s[36:37] offset:512 nt
	global_load_dwordx4 v[206:209], v228, s[36:37] offset:576 nt
	global_load_dwordx4 v[210:213], v229, s[36:37] offset:0 nt
	global_load_dwordx4 v[214:217], v229, s[36:37] offset:64 nt
	global_load_dwordx4 v[218:221], v229, s[36:37] offset:512 nt
	global_load_dwordx4 v[222:225], v229, s[36:37] offset:576 nt
	s_waitcnt vmcnt(15)
	v_pk_add_f32 v[124:125], v[124:125], v[160:161]
	v_pk_add_f32 v[126:127], v[126:127], v[162:163]
	global_store_dwordx4 v226, v[124:127], s[26:27] offset:0
	s_waitcnt vmcnt(15)
	v_pk_add_f32 v[120:121], v[120:121], v[164:165]
	v_pk_add_f32 v[122:123], v[122:123], v[166:167]
	global_store_dwordx4 v226, v[120:123], s[26:27] offset:64
	s_waitcnt vmcnt(15)
	v_pk_add_f32 v[116:117], v[116:117], v[168:169]
	v_pk_add_f32 v[118:119], v[118:119], v[170:171]
	global_store_dwordx4 v226, v[116:119], s[26:27] offset:512
	s_waitcnt vmcnt(15)
	v_pk_add_f32 v[104:105], v[104:105], v[172:173]
	v_pk_add_f32 v[106:107], v[106:107], v[174:175]
	global_store_dwordx4 v226, v[104:107], s[26:27] offset:576
	s_waitcnt vmcnt(15)
	v_pk_add_f32 v[112:113], v[112:113], v[176:177]
	v_pk_add_f32 v[114:115], v[114:115], v[178:179]
	global_store_dwordx4 v227, v[112:115], s[26:27] offset:0
	s_waitcnt vmcnt(15)
	v_pk_add_f32 v[108:109], v[108:109], v[180:181]
	v_pk_add_f32 v[110:111], v[110:111], v[182:183]
	global_store_dwordx4 v227, v[108:111], s[26:27] offset:64
	s_waitcnt vmcnt(15)
	v_pk_add_f32 v[100:101], v[100:101], v[184:185]
	v_pk_add_f32 v[102:103], v[102:103], v[186:187]
	global_store_dwordx4 v227, v[100:103], s[26:27] offset:512
	s_waitcnt vmcnt(15)
	v_pk_add_f32 v[88:89], v[88:89], v[188:189]
	v_pk_add_f32 v[90:91], v[90:91], v[190:191]
	global_store_dwordx4 v227, v[88:91], s[26:27] offset:576
	s_waitcnt vmcnt(15)
	v_pk_add_f32 v[96:97], v[96:97], v[192:193]
	v_pk_add_f32 v[98:99], v[98:99], v[194:195]
	global_store_dwordx4 v228, v[96:99], s[26:27] offset:0
	s_waitcnt vmcnt(15)
	v_pk_add_f32 v[92:93], v[92:93], v[196:197]
	v_pk_add_f32 v[94:95], v[94:95], v[198:199]
	global_store_dwordx4 v228, v[92:95], s[26:27] offset:64
	s_waitcnt vmcnt(15)
	v_pk_add_f32 v[84:85], v[84:85], v[200:201]
	v_pk_add_f32 v[86:87], v[86:87], v[202:203]
	global_store_dwordx4 v228, v[84:87], s[26:27] offset:512
	s_waitcnt vmcnt(15)
	v_pk_add_f32 v[72:73], v[72:73], v[206:207]
	v_pk_add_f32 v[74:75], v[74:75], v[208:209]
	global_store_dwordx4 v228, v[72:75], s[26:27] offset:576
	s_waitcnt vmcnt(15)
	v_pk_add_f32 v[80:81], v[80:81], v[210:211]
	v_pk_add_f32 v[82:83], v[82:83], v[212:213]
	global_store_dwordx4 v229, v[80:83], s[26:27] offset:0
	s_waitcnt vmcnt(15)
	v_pk_add_f32 v[76:77], v[76:77], v[214:215]
	v_pk_add_f32 v[78:79], v[78:79], v[216:217]
	global_store_dwordx4 v229, v[76:79], s[26:27] offset:64
	s_waitcnt vmcnt(15)
	v_pk_add_f32 v[68:69], v[68:69], v[218:219]
	v_pk_add_f32 v[70:71], v[70:71], v[220:221]
	global_store_dwordx4 v229, v[68:71], s[26:27] offset:512
	s_waitcnt vmcnt(15)
	v_pk_add_f32 v[64:65], v[64:65], v[222:223]
	v_pk_add_f32 v[66:67], v[66:67], v[224:225]
	global_store_dwordx4 v229, v[64:67], s[26:27] offset:576
	global_load_dwordx4 v[160:163], v230, s[36:37] offset:0 nt
	global_load_dwordx4 v[164:167], v230, s[36:37] offset:64 nt
	global_load_dwordx4 v[168:171], v230, s[36:37] offset:512 nt
	global_load_dwordx4 v[172:175], v230, s[36:37] offset:576 nt
	global_load_dwordx4 v[176:179], v231, s[36:37] offset:0 nt
	global_load_dwordx4 v[180:183], v231, s[36:37] offset:64 nt
	global_load_dwordx4 v[184:187], v231, s[36:37] offset:512 nt
	global_load_dwordx4 v[188:191], v231, s[36:37] offset:576 nt
	global_load_dwordx4 v[192:195], v232, s[36:37] offset:0 nt
	global_load_dwordx4 v[196:199], v232, s[36:37] offset:64 nt
	global_load_dwordx4 v[200:203], v232, s[36:37] offset:512 nt
	global_load_dwordx4 v[206:209], v232, s[36:37] offset:576 nt
	global_load_dwordx4 v[210:213], v233, s[36:37] offset:0 nt
	global_load_dwordx4 v[214:217], v233, s[36:37] offset:64 nt
	global_load_dwordx4 v[218:221], v233, s[36:37] offset:512 nt
	global_load_dwordx4 v[222:225], v233, s[36:37] offset:576 nt
	s_waitcnt vmcnt(15)
	v_pk_add_f32 v[60:61], v[60:61], v[160:161]
	v_pk_add_f32 v[62:63], v[62:63], v[162:163]
	global_store_dwordx4 v230, v[60:63], s[26:27] offset:0
	s_waitcnt vmcnt(15)
	v_pk_add_f32 v[56:57], v[56:57], v[164:165]
	v_pk_add_f32 v[58:59], v[58:59], v[166:167]
	global_store_dwordx4 v230, v[56:59], s[26:27] offset:64
	s_waitcnt vmcnt(15)
	v_pk_add_f32 v[52:53], v[52:53], v[168:169]
	v_pk_add_f32 v[54:55], v[54:55], v[170:171]
	global_store_dwordx4 v230, v[52:55], s[26:27] offset:512
	s_waitcnt vmcnt(15)
	v_pk_add_f32 v[40:41], v[40:41], v[172:173]
	v_pk_add_f32 v[42:43], v[42:43], v[174:175]
	global_store_dwordx4 v230, v[40:43], s[26:27] offset:576
	s_waitcnt vmcnt(15)
	v_pk_add_f32 v[48:49], v[48:49], v[176:177]
	v_pk_add_f32 v[50:51], v[50:51], v[178:179]
	global_store_dwordx4 v231, v[48:51], s[26:27] offset:0
	s_waitcnt vmcnt(15)
	v_pk_add_f32 v[44:45], v[44:45], v[180:181]
	v_pk_add_f32 v[46:47], v[46:47], v[182:183]
	global_store_dwordx4 v231, v[44:47], s[26:27] offset:64
	s_waitcnt vmcnt(15)
	v_pk_add_f32 v[36:37], v[36:37], v[184:185]
	v_pk_add_f32 v[38:39], v[38:39], v[186:187]
	global_store_dwordx4 v231, v[36:39], s[26:27] offset:512
	s_waitcnt vmcnt(15)
	v_pk_add_f32 v[24:25], v[24:25], v[188:189]
	v_pk_add_f32 v[26:27], v[26:27], v[190:191]
	global_store_dwordx4 v231, v[24:27], s[26:27] offset:576
	s_waitcnt vmcnt(15)
	v_pk_add_f32 v[32:33], v[32:33], v[192:193]
	v_pk_add_f32 v[34:35], v[34:35], v[194:195]
	global_store_dwordx4 v232, v[32:35], s[26:27] offset:0
	s_waitcnt vmcnt(15)
	v_pk_add_f32 v[28:29], v[28:29], v[196:197]
	v_pk_add_f32 v[30:31], v[30:31], v[198:199]
	global_store_dwordx4 v232, v[28:31], s[26:27] offset:64
	s_waitcnt vmcnt(15)
	v_pk_add_f32 v[20:21], v[20:21], v[200:201]
	v_pk_add_f32 v[22:23], v[22:23], v[202:203]
	global_store_dwordx4 v232, v[20:23], s[26:27] offset:512
	s_waitcnt vmcnt(15)
	v_pk_add_f32 v[8:9], v[8:9], v[206:207]
	v_pk_add_f32 v[10:11], v[10:11], v[208:209]
	global_store_dwordx4 v232, v[8:11], s[26:27] offset:576
	s_waitcnt vmcnt(15)
	v_pk_add_f32 v[16:17], v[16:17], v[210:211]
	v_pk_add_f32 v[18:19], v[18:19], v[212:213]
	global_store_dwordx4 v233, v[16:19], s[26:27] offset:0
	s_waitcnt vmcnt(15)
	v_pk_add_f32 v[12:13], v[12:13], v[214:215]
	v_pk_add_f32 v[14:15], v[14:15], v[216:217]
	global_store_dwordx4 v233, v[12:15], s[26:27] offset:64
	s_waitcnt vmcnt(15)
	v_pk_add_f32 v[4:5], v[4:5], v[218:219]
	v_pk_add_f32 v[6:7], v[6:7], v[220:221]
	global_store_dwordx4 v233, v[4:7], s[26:27] offset:512
	s_waitcnt vmcnt(15)
	v_pk_add_f32 v[0:1], v[0:1], v[222:223]
	v_pk_add_f32 v[2:3], v[2:3], v[224:225]
	global_store_dwordx4 v233, v[0:3], s[26:27] offset:576
	s_cbranch_vccnz .LBB0_556
	s_andn2_b64 vcc, exec, s[6:7]
	s_cbranch_vccnz .LBB0_555
	s_barrier
	s_branch .LBB0_555

.LBB0_625:
	s_cmp_lt_i32 s30, 6
	s_cselect_b64 s[0:1], -1, 0
	s_and_b64 s[4:5], s[0:1], s[4:5]
	s_andn2_b64 vcc, exec, s[4:5]
	s_cbranch_vccnz .LBB0_629
	s_lshl_b32 s0, s2, 3
	s_add_i32 s6, s33, s0
	s_cmpk_gt_i32 s6, 0x3fff
	s_cbranch_scc1 .LBB0_629
	s_waitcnt lgkmcnt(0)
	v_lshlrev_b32_e32 v0, 4, v204
	v_lshlrev_b32_e32 v1, 3, v204
	v_mov_b32_e32 v28, 0x358637bd
	s_add_u32 s0, s24, 0x1000
	s_addc_u32 s1, s25, 0
	global_load_dwordx4 v[96:99], v0, s[0:1] offset:-4096
	global_load_dwordx4 v[100:103], v0, s[0:1] offset:-3072
	global_load_dwordx4 v[104:107], v0, s[0:1] offset:-2048
	global_load_dwordx4 v[108:111], v0, s[0:1] offset:-1024
	global_load_dwordx4 v[112:115], v0, s[0:1] offset:0
	global_load_dwordx4 v[116:119], v0, s[0:1] offset:1024
	global_load_dwordx4 v[120:123], v0, s[0:1] offset:2048
	global_load_dwordx4 v[124:127], v0, s[0:1] offset:3072
	s_lshl_b32 s3, s6, 13
	s_add_u32 s8, s28, s3
	s_addc_u32 s9, s29, 0
	s_add_u32 s8, s8, 0xa201000
	s_addc_u32 s9, s9, 0
	s_lshl_b32 s3, s6, 12
	s_add_u32 s12, s28, s3
	s_addc_u32 s13, s29, 0
	s_add_u32 s12, s12, 0x6200000
	s_addc_u32 s13, s13, 0
	s_lshl_b32 s7, s34, 3
	s_lshl_b32 s14, s7, 13
	s_lshl_b32 s15, s7, 12
	global_load_dwordx4 v[32:35], v0, s[8:9] offset:-4096 nt
	global_load_dwordx4 v[36:39], v0, s[8:9] offset:-3072 nt
	global_load_dwordx4 v[40:43], v0, s[8:9] offset:-2048 nt
	global_load_dwordx4 v[44:47], v0, s[8:9] offset:-1024 nt
	global_load_dwordx4 v[48:51], v0, s[8:9] offset:0 nt
	global_load_dwordx4 v[52:55], v0, s[8:9] offset:1024 nt
	global_load_dwordx4 v[56:59], v0, s[8:9] offset:2048 nt
	global_load_dwordx4 v[60:63], v0, s[8:9] offset:3072 nt
	s_mov_b32 s3, 0
.Lp5r_loop:
	s_add_i32 s6, s6, s7
	s_cmp_lt_i32 s6, 0x4000
	s_cselect_b32 s0, 1, 0
	s_cbranch_scc0 .Lp5r_a_nonext
	s_add_u32 s8, s8, s14
	s_addc_u32 s9, s9, 0
	global_load_dwordx4 v[64:67], v0, s[8:9] offset:-4096 nt
	global_load_dwordx4 v[68:71], v0, s[8:9] offset:-3072 nt
	global_load_dwordx4 v[72:75], v0, s[8:9] offset:-2048 nt
	global_load_dwordx4 v[76:79], v0, s[8:9] offset:-1024 nt
	global_load_dwordx4 v[80:83], v0, s[8:9] offset:0 nt
	global_load_dwordx4 v[84:87], v0, s[8:9] offset:1024 nt
	global_load_dwordx4 v[88:91], v0, s[8:9] offset:2048 nt
	global_load_dwordx4 v[92:95], v0, s[8:9] offset:3072 nt

.Lp5r_a_go:
	v_pk_mul_f32 v[2:3], v[32:33], v[32:33]
	v_pk_mul_f32 v[4:5], v[34:35], v[34:35]
	v_pk_fma_f32 v[2:3], v[36:37], v[36:37], v[2:3]
	v_pk_fma_f32 v[4:5], v[38:39], v[38:39], v[4:5]
	v_pk_fma_f32 v[2:3], v[40:41], v[40:41], v[2:3]
	v_pk_fma_f32 v[4:5], v[42:43], v[42:43], v[4:5]
	v_pk_fma_f32 v[2:3], v[44:45], v[44:45], v[2:3]
	v_pk_fma_f32 v[4:5], v[46:47], v[46:47], v[4:5]
	v_pk_fma_f32 v[2:3], v[48:49], v[48:49], v[2:3]
	v_pk_fma_f32 v[4:5], v[50:51], v[50:51], v[4:5]
	v_pk_fma_f32 v[2:3], v[52:53], v[52:53], v[2:3]
	v_pk_fma_f32 v[4:5], v[54:55], v[54:55], v[4:5]
	v_pk_fma_f32 v[2:3], v[56:57], v[56:57], v[2:3]
	v_pk_fma_f32 v[4:5], v[58:59], v[58:59], v[4:5]
	v_pk_fma_f32 v[2:3], v[60:61], v[60:61], v[2:3]
	v_pk_fma_f32 v[4:5], v[62:63], v[62:63], v[4:5]
	v_pk_add_f32 v[2:3], v[2:3], v[4:5]
	s_nop 0
	v_add_f32_e32 v2, v2, v3
	s_nop 1
	v_add_f32_dpp v3, v2, v2 quad_perm:[1,0,3,2] row_mask:0xf bank_mask:0xf
	s_nop 1
	v_add_f32_dpp v2, v3, v3 quad_perm:[2,3,0,1] row_mask:0xf bank_mask:0xf
	s_nop 1
	v_add_f32_dpp v3, v2, v2 row_ror:4 row_mask:0xf bank_mask:0xf
	s_nop 1
	v_add_f32_dpp v2, v3, v3 row_ror:8 row_mask:0xf bank_mask:0xf
	s_nop 1
	v_readlane_b32 s100, v2, 0
	v_readlane_b32 s101, v2, 16
	v_readlane_b32 vcc_lo, v2, 32
	v_readlane_b32 vcc_hi, v2, 48
	v_mov_b32_e32 v3, s100
	v_add_f32_e32 v3, s101, v3
	v_add_f32_e32 v3, vcc_lo, v3
	v_add_f32_e32 v3, vcc_hi, v3
	v_fmamk_f32 v2, v3, 0x3a000000, v28
	v_mul_f32_e32 v3, 0x4b800000, v2
	v_cmp_gt_f32_e32 vcc, 0x800000, v2
	s_nop 1
	v_cndmask_b32_e32 v2, v2, v3, vcc
	v_rsq_f32_e32 v2, v2
	s_nop 0
	v_mul_f32_e32 v3, 0x45800000, v2
	v_cndmask_b32_e32 v2, v2, v3, vcc
	v_pk_mul_f32 v[32:33], v[32:33], v[2:3] op_sel_hi:[1,0]
	v_pk_mul_f32 v[34:35], v[34:35], v[2:3] op_sel_hi:[1,0]
	v_pk_mul_f32 v[32:33], v[32:33], v[96:97]
	v_pk_mul_f32 v[34:35], v[34:35], v[98:99]
	v_cvt_pk_bf16_f32 v6, v32, v33
	v_cvt_pk_bf16_f32 v7, v34, v35
	global_store_dwordx2 v1, v[6:7], s[12:13]
	v_pk_mul_f32 v[36:37], v[36:37], v[2:3] op_sel_hi:[1,0]
	v_pk_mul_f32 v[38:39], v[38:39], v[2:3] op_sel_hi:[1,0]
	v_pk_mul_f32 v[36:37], v[36:37], v[100:101]
	v_pk_mul_f32 v[38:39], v[38:39], v[102:103]
	v_cvt_pk_bf16_f32 v8, v36, v37
	v_cvt_pk_bf16_f32 v9, v38, v39
	global_store_dwordx2 v1, v[8:9], s[12:13] offset:512
	v_pk_mul_f32 v[40:41], v[40:41], v[2:3] op_sel_hi:[1,0]
	v_pk_mul_f32 v[42:43], v[42:43], v[2:3] op_sel_hi:[1,0]
	v_pk_mul_f32 v[40:41], v[40:41], v[104:105]
	v_pk_mul_f32 v[42:43], v[42:43], v[106:107]
	v_cvt_pk_bf16_f32 v6, v40, v41
	v_cvt_pk_bf16_f32 v7, v42, v43
	global_store_dwordx2 v1, v[6:7], s[12:13] offset:1024
	v_pk_mul_f32 v[44:45], v[44:45], v[2:3] op_sel_hi:[1,0]
	v_pk_mul_f32 v[46:47], v[46:47], v[2:3] op_sel_hi:[1,0]
	v_pk_mul_f32 v[44:45], v[44:45], v[108:109]
	v_pk_mul_f32 v[46:47], v[46:47], v[110:111]
	v_cvt_pk_bf16_f32 v8, v44, v45
	v_cvt_pk_bf16_f32 v9, v46, v47
	global_store_dwordx2 v1, v[8:9], s[12:13] offset:1536
	v_pk_mul_f32 v[48:49], v[48:49], v[2:3] op_sel_hi:[1,0]
	v_pk_mul_f32 v[50:51], v[50:51], v[2:3] op_sel_hi:[1,0]
	v_pk_mul_f32 v[48:49], v[48:49], v[112:113]
	v_pk_mul_f32 v[50:51], v[50:51], v[114:115]
	v_cvt_pk_bf16_f32 v6, v48, v49
	v_cvt_pk_bf16_f32 v7, v50, v51
	global_store_dwordx2 v1, v[6:7], s[12:13] offset:2048
	v_pk_mul_f32 v[52:53], v[52:53], v[2:3] op_sel_hi:[1,0]
	v_pk_mul_f32 v[54:55], v[54:55], v[2:3] op_sel_hi:[1,0]
	v_pk_mul_f32 v[52:53], v[52:53], v[116:117]
	v_pk_mul_f32 v[54:55], v[54:55], v[118:119]
	v_cvt_pk_bf16_f32 v8, v52, v53
	v_cvt_pk_bf16_f32 v9, v54, v55
	global_store_dwordx2 v1, v[8:9], s[12:13] offset:2560
	v_pk_mul_f32 v[56:57], v[56:57], v[2:3] op_sel_hi:[1,0]
	v_pk_mul_f32 v[58:59], v[58:59], v[2:3] op_sel_hi:[1,0]
	v_pk_mul_f32 v[56:57], v[56:57], v[120:121]
	v_pk_mul_f32 v[58:59], v[58:59], v[122:123]
	v_cvt_pk_bf16_f32 v6, v56, v57
	v_cvt_pk_bf16_f32 v7, v58, v59
	global_store_dwordx2 v1, v[6:7], s[12:13] offset:3072
	v_pk_mul_f32 v[60:61], v[60:61], v[2:3] op_sel_hi:[1,0]
	v_pk_mul_f32 v[62:63], v[62:63], v[2:3] op_sel_hi:[1,0]
	v_pk_mul_f32 v[60:61], v[60:61], v[124:125]
	v_pk_mul_f32 v[62:63], v[62:63], v[126:127]
	v_cvt_pk_bf16_f32 v8, v60, v61
	v_cvt_pk_bf16_f32 v9, v62, v63
	global_store_dwordx2 v1, v[8:9], s[12:13] offset:3584
	s_add_u32 s12, s12, s15
	s_addc_u32 s13, s13, 0
	s_mov_b32 s3, 1
	s_cmp_eq_u32 s0, 0
	s_cbranch_scc1 .LBB0_629
	s_add_i32 s6, s6, s7
	s_cmp_lt_i32 s6, 0x4000
	s_cselect_b32 s0, 1, 0
	s_cbranch_scc0 .Lp5r_b_nonext
	s_add_u32 s8, s8, s14
	s_addc_u32 s9, s9, 0
	global_load_dwordx4 v[32:35], v0, s[8:9] offset:-4096 nt
	global_load_dwordx4 v[36:39], v0, s[8:9] offset:-3072 nt
	global_load_dwordx4 v[40:43], v0, s[8:9] offset:-2048 nt
	global_load_dwordx4 v[44:47], v0, s[8:9] offset:-1024 nt
	global_load_dwordx4 v[48:51], v0, s[8:9] offset:0 nt
	global_load_dwordx4 v[52:55], v0, s[8:9] offset:1024 nt
	global_load_dwordx4 v[56:59], v0, s[8:9] offset:2048 nt
	global_load_dwordx4 v[60:63], v0, s[8:9] offset:3072 nt

.LBB0_779:
	v_lshl_add_u32 v152, s68, 8, v142
	v_lshl_or_b32 v154, s69, 8, v144
	v_ashrrev_i32_e32 v153, 31, v152
	v_ashrrev_i32_e32 v155, 31, v154
	v_lshlrev_b64 v[140:141], 11, v[152:153]
	v_lshl_add_u64 v[140:141], v[140:141], 0, v[154:155]
	v_lshlrev_b64 v[140:141], 2, v[140:141]
	s_and_b64 vcc, exec, s[4:5]
	s_mov_b64 s[4:5], -1
	v_mov_b32_e32 v226, v140
	v_add_u32_e32 v227, 0x20000, v140
	v_add_u32_e32 v228, 0x40000, v140
	v_add_u32_e32 v229, 0x60000, v140
	v_add_u32_e32 v230, 0x100000, v140
	v_add_u32_e32 v231, 0x120000, v140
	v_add_u32_e32 v232, 0x140000, v140
	v_add_u32_e32 v233, 0x160000, v140
	global_load_dwordx4 v[160:163], v226, s[26:27] offset:0 nt
	global_load_dwordx4 v[164:167], v226, s[26:27] offset:64 nt
	global_load_dwordx4 v[168:171], v226, s[26:27] offset:512 nt
	global_load_dwordx4 v[172:175], v226, s[26:27] offset:576 nt
	global_load_dwordx4 v[176:179], v227, s[26:27] offset:0 nt
	global_load_dwordx4 v[180:183], v227, s[26:27] offset:64 nt
	global_load_dwordx4 v[184:187], v227, s[26:27] offset:512 nt
	global_load_dwordx4 v[188:191], v227, s[26:27] offset:576 nt
	global_load_dwordx4 v[192:195], v228, s[26:27] offset:0 nt
	global_load_dwordx4 v[196:199], v228, s[26:27] offset:64 nt
	global_load_dwordx4 v[200:203], v228, s[26:27] offset:512 nt
	global_load_dwordx4 v[206:209], v228, s[26:27] offset:576 nt
	global_load_dwordx4 v[210:213], v229, s[26:27] offset:0 nt
	global_load_dwordx4 v[214:217], v229, s[26:27] offset:64 nt
	global_load_dwordx4 v[218:221], v229, s[26:27] offset:512 nt
	global_load_dwordx4 v[222:225], v229, s[26:27] offset:576 nt
	s_waitcnt vmcnt(15)
	v_pk_add_f32 v[124:125], v[124:125], v[160:161]
	v_pk_add_f32 v[126:127], v[126:127], v[162:163]
	global_store_dwordx4 v226, v[124:127], s[58:59] offset:0
	s_waitcnt vmcnt(15)
	v_pk_add_f32 v[120:121], v[120:121], v[164:165]
	v_pk_add_f32 v[122:123], v[122:123], v[166:167]
	global_store_dwordx4 v226, v[120:123], s[58:59] offset:64
	s_waitcnt vmcnt(15)
	v_pk_add_f32 v[116:117], v[116:117], v[168:169]
	v_pk_add_f32 v[118:119], v[118:119], v[170:171]
	global_store_dwordx4 v226, v[116:119], s[58:59] offset:512
	s_waitcnt vmcnt(15)
	v_pk_add_f32 v[104:105], v[104:105], v[172:173]
	v_pk_add_f32 v[106:107], v[106:107], v[174:175]
	global_store_dwordx4 v226, v[104:107], s[58:59] offset:576
	s_waitcnt vmcnt(15)
	v_pk_add_f32 v[112:113], v[112:113], v[176:177]
	v_pk_add_f32 v[114:115], v[114:115], v[178:179]
	global_store_dwordx4 v227, v[112:115], s[58:59] offset:0
	s_waitcnt vmcnt(15)
	v_pk_add_f32 v[108:109], v[108:109], v[180:181]
	v_pk_add_f32 v[110:111], v[110:111], v[182:183]
	global_store_dwordx4 v227, v[108:111], s[58:59] offset:64
	s_waitcnt vmcnt(15)
	v_pk_add_f32 v[100:101], v[100:101], v[184:185]
	v_pk_add_f32 v[102:103], v[102:103], v[186:187]
	global_store_dwordx4 v227, v[100:103], s[58:59] offset:512
	s_waitcnt vmcnt(15)
	v_pk_add_f32 v[88:89], v[88:89], v[188:189]
	v_pk_add_f32 v[90:91], v[90:91], v[190:191]
	global_store_dwordx4 v227, v[88:91], s[58:59] offset:576
	s_waitcnt vmcnt(15)
	v_pk_add_f32 v[96:97], v[96:97], v[192:193]
	v_pk_add_f32 v[98:99], v[98:99], v[194:195]
	global_store_dwordx4 v228, v[96:99], s[58:59] offset:0
	s_waitcnt vmcnt(15)
	v_pk_add_f32 v[92:93], v[92:93], v[196:197]
	v_pk_add_f32 v[94:95], v[94:95], v[198:199]
	global_store_dwordx4 v228, v[92:95], s[58:59] offset:64
	s_waitcnt vmcnt(15)
	v_pk_add_f32 v[84:85], v[84:85], v[200:201]
	v_pk_add_f32 v[86:87], v[86:87], v[202:203]
	global_store_dwordx4 v228, v[84:87], s[58:59] offset:512
	s_waitcnt vmcnt(15)
	v_pk_add_f32 v[72:73], v[72:73], v[206:207]
	v_pk_add_f32 v[74:75], v[74:75], v[208:209]
	global_store_dwordx4 v228, v[72:75], s[58:59] offset:576
	s_waitcnt vmcnt(15)
	v_pk_add_f32 v[80:81], v[80:81], v[210:211]
	v_pk_add_f32 v[82:83], v[82:83], v[212:213]
	global_store_dwordx4 v229, v[80:83], s[58:59] offset:0
	s_waitcnt vmcnt(15)
	v_pk_add_f32 v[76:77], v[76:77], v[214:215]
	v_pk_add_f32 v[78:79], v[78:79], v[216:217]
	global_store_dwordx4 v229, v[76:79], s[58:59] offset:64
	s_waitcnt vmcnt(15)
	v_pk_add_f32 v[68:69], v[68:69], v[218:219]
	v_pk_add_f32 v[70:71], v[70:71], v[220:221]
	global_store_dwordx4 v229, v[68:71], s[58:59] offset:512
	s_waitcnt vmcnt(15)
	v_pk_add_f32 v[64:65], v[64:65], v[222:223]
	v_pk_add_f32 v[66:67], v[66:67], v[224:225]
	global_store_dwordx4 v229, v[64:67], s[58:59] offset:576
	global_load_dwordx4 v[160:163], v230, s[26:27] offset:0 nt
	global_load_dwordx4 v[164:167], v230, s[26:27] offset:64 nt
	global_load_dwordx4 v[168:171], v230, s[26:27] offset:512 nt
	global_load_dwordx4 v[172:175], v230, s[26:27] offset:576 nt
	global_load_dwordx4 v[176:179], v231, s[26:27] offset:0 nt
	global_load_dwordx4 v[180:183], v231, s[26:27] offset:64 nt
	global_load_dwordx4 v[184:187], v231, s[26:27] offset:512 nt
	global_load_dwordx4 v[188:191], v231, s[26:27] offset:576 nt
	global_load_dwordx4 v[192:195], v232, s[26:27] offset:0 nt
	global_load_dwordx4 v[196:199], v232, s[26:27] offset:64 nt
	global_load_dwordx4 v[200:203], v232, s[26:27] offset:512 nt
	global_load_dwordx4 v[206:209], v232, s[26:27] offset:576 nt
	global_load_dwordx4 v[210:213], v233, s[26:27] offset:0 nt
	global_load_dwordx4 v[214:217], v233, s[26:27] offset:64 nt
	global_load_dwordx4 v[218:221], v233, s[26:27] offset:512 nt
	global_load_dwordx4 v[222:225], v233, s[26:27] offset:576 nt
	s_waitcnt vmcnt(15)
	v_pk_add_f32 v[60:61], v[60:61], v[160:161]
	v_pk_add_f32 v[62:63], v[62:63], v[162:163]
	global_store_dwordx4 v230, v[60:63], s[58:59] offset:0
	s_waitcnt vmcnt(15)
	v_pk_add_f32 v[56:57], v[56:57], v[164:165]
	v_pk_add_f32 v[58:59], v[58:59], v[166:167]
	global_store_dwordx4 v230, v[56:59], s[58:59] offset:64
	s_waitcnt vmcnt(15)
	v_pk_add_f32 v[52:53], v[52:53], v[168:169]
	v_pk_add_f32 v[54:55], v[54:55], v[170:171]
	global_store_dwordx4 v230, v[52:55], s[58:59] offset:512
	s_waitcnt vmcnt(15)
	v_pk_add_f32 v[40:41], v[40:41], v[172:173]
	v_pk_add_f32 v[42:43], v[42:43], v[174:175]
	global_store_dwordx4 v230, v[40:43], s[58:59] offset:576
	s_waitcnt vmcnt(15)
	v_pk_add_f32 v[48:49], v[48:49], v[176:177]
	v_pk_add_f32 v[50:51], v[50:51], v[178:179]
	global_store_dwordx4 v231, v[48:51], s[58:59] offset:0
	s_waitcnt vmcnt(15)
	v_pk_add_f32 v[44:45], v[44:45], v[180:181]
	v_pk_add_f32 v[46:47], v[46:47], v[182:183]
	global_store_dwordx4 v231, v[44:47], s[58:59] offset:64
	s_waitcnt vmcnt(15)
	v_pk_add_f32 v[36:37], v[36:37], v[184:185]
	v_pk_add_f32 v[38:39], v[38:39], v[186:187]
	global_store_dwordx4 v231, v[36:39], s[58:59] offset:512
	s_waitcnt vmcnt(15)
	v_pk_add_f32 v[24:25], v[24:25], v[188:189]
	v_pk_add_f32 v[26:27], v[26:27], v[190:191]
	global_store_dwordx4 v231, v[24:27], s[58:59] offset:576
	s_waitcnt vmcnt(15)
	v_pk_add_f32 v[32:33], v[32:33], v[192:193]
	v_pk_add_f32 v[34:35], v[34:35], v[194:195]
	global_store_dwordx4 v232, v[32:35], s[58:59] offset:0
	s_waitcnt vmcnt(15)
	v_pk_add_f32 v[28:29], v[28:29], v[196:197]
	v_pk_add_f32 v[30:31], v[30:31], v[198:199]
	global_store_dwordx4 v232, v[28:31], s[58:59] offset:64
	s_waitcnt vmcnt(15)
	v_pk_add_f32 v[20:21], v[20:21], v[200:201]
	v_pk_add_f32 v[22:23], v[22:23], v[202:203]
	global_store_dwordx4 v232, v[20:23], s[58:59] offset:512
	s_waitcnt vmcnt(15)
	v_pk_add_f32 v[8:9], v[8:9], v[206:207]
	v_pk_add_f32 v[10:11], v[10:11], v[208:209]
	global_store_dwordx4 v232, v[8:11], s[58:59] offset:576
	s_waitcnt vmcnt(15)
	v_pk_add_f32 v[16:17], v[16:17], v[210:211]
	v_pk_add_f32 v[18:19], v[18:19], v[212:213]
	global_store_dwordx4 v233, v[16:19], s[58:59] offset:0
	s_waitcnt vmcnt(15)
	v_pk_add_f32 v[12:13], v[12:13], v[214:215]
	v_pk_add_f32 v[14:15], v[14:15], v[216:217]
	global_store_dwordx4 v233, v[12:15], s[58:59] offset:64
	s_waitcnt vmcnt(15)
	v_pk_add_f32 v[4:5], v[4:5], v[218:219]
	v_pk_add_f32 v[6:7], v[6:7], v[220:221]
	global_store_dwordx4 v233, v[4:7], s[58:59] offset:512
	s_waitcnt vmcnt(15)
	v_pk_add_f32 v[0:1], v[0:1], v[222:223]
	v_pk_add_f32 v[2:3], v[2:3], v[224:225]
	global_store_dwordx4 v233, v[0:3], s[58:59] offset:576
	s_cbranch_vccnz .LBB0_764
	s_andn2_b64 vcc, exec, s[12:13]
	s_cbranch_vccnz .LBB0_763
	s_barrier
	s_branch .LBB0_763

.LBB0_837:
	s_cmp_lt_i32 s30, 9
	s_cselect_b64 s[4:5], -1, 0
	s_and_b64 s[0:1], s[4:5], s[0:1]
	s_andn2_b64 vcc, exec, s[0:1]
	s_cbranch_vccnz .LBB0_841
	s_lshl_b32 s0, s2, 3
	s_add_i32 s0, s33, s0
	s_cmpk_gt_i32 s0, 0x3fff
	s_cbranch_scc1 .LBB0_841
	s_mov_b32 s6, s0
	s_waitcnt lgkmcnt(0)
	v_lshlrev_b32_e32 v0, 4, v204
	v_mov_b32_e32 v28, 0x358637bd
	s_add_u32 s0, s56, 0x1000
	s_addc_u32 s1, s57, 0
	global_load_dwordx4 v[96:99], v0, s[0:1] offset:-4096
	global_load_dwordx4 v[100:103], v0, s[0:1] offset:-3072
	global_load_dwordx4 v[104:107], v0, s[0:1] offset:-2048
	global_load_dwordx4 v[108:111], v0, s[0:1] offset:-1024
	global_load_dwordx4 v[112:115], v0, s[0:1] offset:0
	global_load_dwordx4 v[116:119], v0, s[0:1] offset:1024
	global_load_dwordx4 v[120:123], v0, s[0:1] offset:2048
	global_load_dwordx4 v[124:127], v0, s[0:1] offset:3072
	s_lshl_b32 s3, s6, 13
	s_add_u32 s8, s58, s3
	s_addc_u32 s9, s59, 0
	s_add_u32 s8, s8, 0x1000
	s_addc_u32 s9, s9, 0
	s_mov_b64 s[12:13], s[8:9]
	s_lshl_b32 s7, s34, 3
	s_lshl_b32 s14, s7, 13
	global_load_dwordx4 v[32:35], v0, s[8:9] offset:-4096 nt
	global_load_dwordx4 v[36:39], v0, s[8:9] offset:-3072 nt
	global_load_dwordx4 v[40:43], v0, s[8:9] offset:-2048 nt
	global_load_dwordx4 v[44:47], v0, s[8:9] offset:-1024 nt
	global_load_dwordx4 v[48:51], v0, s[8:9] offset:0 nt
	global_load_dwordx4 v[52:55], v0, s[8:9] offset:1024 nt
	global_load_dwordx4 v[56:59], v0, s[8:9] offset:2048 nt
	global_load_dwordx4 v[60:63], v0, s[8:9] offset:3072 nt
	s_mov_b32 s3, 0

.Lp8r_a_go:
	v_pk_mul_f32 v[2:3], v[32:33], v[32:33]
	v_pk_mul_f32 v[4:5], v[34:35], v[34:35]
	v_pk_fma_f32 v[2:3], v[36:37], v[36:37], v[2:3]
	v_pk_fma_f32 v[4:5], v[38:39], v[38:39], v[4:5]
	v_pk_fma_f32 v[2:3], v[40:41], v[40:41], v[2:3]
	v_pk_fma_f32 v[4:5], v[42:43], v[42:43], v[4:5]
	v_pk_fma_f32 v[2:3], v[44:45], v[44:45], v[2:3]
	v_pk_fma_f32 v[4:5], v[46:47], v[46:47], v[4:5]
	v_pk_fma_f32 v[2:3], v[48:49], v[48:49], v[2:3]
	v_pk_fma_f32 v[4:5], v[50:51], v[50:51], v[4:5]
	v_pk_fma_f32 v[2:3], v[52:53], v[52:53], v[2:3]
	v_pk_fma_f32 v[4:5], v[54:55], v[54:55], v[4:5]
	v_pk_fma_f32 v[2:3], v[56:57], v[56:57], v[2:3]
	v_pk_fma_f32 v[4:5], v[58:59], v[58:59], v[4:5]
	v_pk_fma_f32 v[2:3], v[60:61], v[60:61], v[2:3]
	v_pk_fma_f32 v[4:5], v[62:63], v[62:63], v[4:5]
	v_pk_add_f32 v[2:3], v[2:3], v[4:5]
	s_nop 0
	v_add_f32_e32 v2, v2, v3
	s_nop 1
	v_add_f32_dpp v3, v2, v2 quad_perm:[1,0,3,2] row_mask:0xf bank_mask:0xf
	s_nop 1
	v_add_f32_dpp v2, v3, v3 quad_perm:[2,3,0,1] row_mask:0xf bank_mask:0xf
	s_nop 1
	v_add_f32_dpp v3, v2, v2 row_ror:4 row_mask:0xf bank_mask:0xf
	s_nop 1
	v_add_f32_dpp v2, v3, v3 row_ror:8 row_mask:0xf bank_mask:0xf
	s_nop 1
	v_readlane_b32 s100, v2, 0
	v_readlane_b32 s101, v2, 16
	v_readlane_b32 vcc_lo, v2, 32
	v_readlane_b32 vcc_hi, v2, 48
	v_mov_b32_e32 v3, s100
	v_add_f32_e32 v3, s101, v3
	v_add_f32_e32 v3, vcc_lo, v3
	v_add_f32_e32 v3, vcc_hi, v3
	v_fmamk_f32 v2, v3, 0x3a000000, v28
	v_mul_f32_e32 v3, 0x4b800000, v2
	v_cmp_gt_f32_e32 vcc, 0x800000, v2
	s_nop 1
	v_cndmask_b32_e32 v2, v2, v3, vcc
	v_rsq_f32_e32 v2, v2
	s_nop 0
	v_mul_f32_e32 v3, 0x45800000, v2
	v_cndmask_b32_e32 v2, v2, v3, vcc
	v_pk_mul_f32 v[32:33], v[32:33], v[2:3] op_sel_hi:[1,0]
	v_pk_mul_f32 v[34:35], v[34:35], v[2:3] op_sel_hi:[1,0]
	v_pk_mul_f32 v[32:33], v[32:33], v[96:97]
	v_pk_mul_f32 v[34:35], v[34:35], v[98:99]
	global_store_dwordx4 v0, v[32:35], s[12:13] offset:-4096 nt
	v_pk_mul_f32 v[36:37], v[36:37], v[2:3] op_sel_hi:[1,0]
	v_pk_mul_f32 v[38:39], v[38:39], v[2:3] op_sel_hi:[1,0]
	v_pk_mul_f32 v[36:37], v[36:37], v[100:101]
	v_pk_mul_f32 v[38:39], v[38:39], v[102:103]
	global_store_dwordx4 v0, v[36:39], s[12:13] offset:-3072 nt
	v_pk_mul_f32 v[40:41], v[40:41], v[2:3] op_sel_hi:[1,0]
	v_pk_mul_f32 v[42:43], v[42:43], v[2:3] op_sel_hi:[1,0]
	v_pk_mul_f32 v[40:41], v[40:41], v[104:105]
	v_pk_mul_f32 v[42:43], v[42:43], v[106:107]
	global_store_dwordx4 v0, v[40:43], s[12:13] offset:-2048 nt
	v_pk_mul_f32 v[44:45], v[44:45], v[2:3] op_sel_hi:[1,0]
	v_pk_mul_f32 v[46:47], v[46:47], v[2:3] op_sel_hi:[1,0]
	v_pk_mul_f32 v[44:45], v[44:45], v[108:109]
	v_pk_mul_f32 v[46:47], v[46:47], v[110:111]
	global_store_dwordx4 v0, v[44:47], s[12:13] offset:-1024 nt
	v_pk_mul_f32 v[48:49], v[48:49], v[2:3] op_sel_hi:[1,0]
	v_pk_mul_f32 v[50:51], v[50:51], v[2:3] op_sel_hi:[1,0]
	v_pk_mul_f32 v[48:49], v[48:49], v[112:113]
	v_pk_mul_f32 v[50:51], v[50:51], v[114:115]
	global_store_dwordx4 v0, v[48:51], s[12:13] offset:0 nt
	v_pk_mul_f32 v[52:53], v[52:53], v[2:3] op_sel_hi:[1,0]
	v_pk_mul_f32 v[54:55], v[54:55], v[2:3] op_sel_hi:[1,0]
	v_pk_mul_f32 v[52:53], v[52:53], v[116:117]
	v_pk_mul_f32 v[54:55], v[54:55], v[118:119]
	global_store_dwordx4 v0, v[52:55], s[12:13] offset:1024 nt
	v_pk_mul_f32 v[56:57], v[56:57], v[2:3] op_sel_hi:[1,0]
	v_pk_mul_f32 v[58:59], v[58:59], v[2:3] op_sel_hi:[1,0]
	v_pk_mul_f32 v[56:57], v[56:57], v[120:121]
	v_pk_mul_f32 v[58:59], v[58:59], v[122:123]
	global_store_dwordx4 v0, v[56:59], s[12:13] offset:2048 nt
	v_pk_mul_f32 v[60:61], v[60:61], v[2:3] op_sel_hi:[1,0]
	v_pk_mul_f32 v[62:63], v[62:63], v[2:3] op_sel_hi:[1,0]
	v_pk_mul_f32 v[60:61], v[60:61], v[124:125]
	v_pk_mul_f32 v[62:63], v[62:63], v[126:127]
	global_store_dwordx4 v0, v[60:63], s[12:13] offset:3072 nt
	s_mov_b64 s[12:13], s[8:9]
	s_mov_b32 s3, 1
	s_cmp_eq_u32 s0, 0
	s_cbranch_scc1 .LBB0_841
	s_add_i32 s6, s6, s7
	s_cmp_lt_i32 s6, 0x4000
	s_cselect_b32 s0, 1, 0
	s_cbranch_scc0 .Lp8r_b_nonext
	s_add_u32 s8, s8, s14
	s_addc_u32 s9, s9, 0
	global_load_dwordx4 v[32:35], v0, s[8:9] offset:-4096 nt
	global_load_dwordx4 v[36:39], v0, s[8:9] offset:-3072 nt
	global_load_dwordx4 v[40:43], v0, s[8:9] offset:-2048 nt
	global_load_dwordx4 v[44:47], v0, s[8:9] offset:-1024 nt
	global_load_dwordx4 v[48:51], v0, s[8:9] offset:0 nt
	global_load_dwordx4 v[52:55], v0, s[8:9] offset:1024 nt
	global_load_dwordx4 v[56:59], v0, s[8:9] offset:2048 nt
	global_load_dwordx4 v[60:63], v0, s[8:9] offset:3072 nt

.Lp8r_b_go:
	v_pk_mul_f32 v[2:3], v[64:65], v[64:65]
	v_pk_mul_f32 v[4:5], v[66:67], v[66:67]
	v_pk_fma_f32 v[2:3], v[68:69], v[68:69], v[2:3]
	v_pk_fma_f32 v[4:5], v[70:71], v[70:71], v[4:5]
	v_pk_fma_f32 v[2:3], v[72:73], v[72:73], v[2:3]
	v_pk_fma_f32 v[4:5], v[74:75], v[74:75], v[4:5]
	v_pk_fma_f32 v[2:3], v[76:77], v[76:77], v[2:3]
	v_pk_fma_f32 v[4:5], v[78:79], v[78:79], v[4:5]
	v_pk_fma_f32 v[2:3], v[80:81], v[80:81], v[2:3]
	v_pk_fma_f32 v[4:5], v[82:83], v[82:83], v[4:5]
	v_pk_fma_f32 v[2:3], v[84:85], v[84:85], v[2:3]
	v_pk_fma_f32 v[4:5], v[86:87], v[86:87], v[4:5]
	v_pk_fma_f32 v[2:3], v[88:89], v[88:89], v[2:3]
	v_pk_fma_f32 v[4:5], v[90:91], v[90:91], v[4:5]
	v_pk_fma_f32 v[2:3], v[92:93], v[92:93], v[2:3]
	v_pk_fma_f32 v[4:5], v[94:95], v[94:95], v[4:5]
	v_pk_add_f32 v[2:3], v[2:3], v[4:5]
	s_nop 0
	v_add_f32_e32 v2, v2, v3
	s_nop 1
	v_add_f32_dpp v3, v2, v2 quad_perm:[1,0,3,2] row_mask:0xf bank_mask:0xf
	s_nop 1
	v_add_f32_dpp v2, v3, v3 quad_perm:[2,3,0,1] row_mask:0xf bank_mask:0xf
	s_nop 1
	v_add_f32_dpp v3, v2, v2 row_ror:4 row_mask:0xf bank_mask:0xf
	s_nop 1
	v_add_f32_dpp v2, v3, v3 row_ror:8 row_mask:0xf bank_mask:0xf
	s_nop 1
	v_readlane_b32 s100, v2, 0
	v_readlane_b32 s101, v2, 16
	v_readlane_b32 vcc_lo, v2, 32
	v_readlane_b32 vcc_hi, v2, 48
	v_mov_b32_e32 v3, s100
	v_add_f32_e32 v3, s101, v3
	v_add_f32_e32 v3, vcc_lo, v3
	v_add_f32_e32 v3, vcc_hi, v3
	v_fmamk_f32 v2, v3, 0x3a000000, v28
	v_mul_f32_e32 v3, 0x4b800000, v2
	v_cmp_gt_f32_e32 vcc, 0x800000, v2
	s_nop 1
	v_cndmask_b32_e32 v2, v2, v3, vcc
	v_rsq_f32_e32 v2, v2
	s_nop 0
	v_mul_f32_e32 v3, 0x45800000, v2
	v_cndmask_b32_e32 v2, v2, v3, vcc
	v_pk_mul_f32 v[64:65], v[64:65], v[2:3] op_sel_hi:[1,0]
	v_pk_mul_f32 v[66:67], v[66:67], v[2:3] op_sel_hi:[1,0]
	v_pk_mul_f32 v[64:65], v[64:65], v[96:97]
	v_pk_mul_f32 v[66:67], v[66:67], v[98:99]
	global_store_dwordx4 v0, v[64:67], s[12:13] offset:-4096 nt
	v_pk_mul_f32 v[68:69], v[68:69], v[2:3] op_sel_hi:[1,0]
	v_pk_mul_f32 v[70:71], v[70:71], v[2:3] op_sel_hi:[1,0]
	v_pk_mul_f32 v[68:69], v[68:69], v[100:101]
	v_pk_mul_f32 v[70:71], v[70:71], v[102:103]
	global_store_dwordx4 v0, v[68:71], s[12:13] offset:-3072 nt
	v_pk_mul_f32 v[72:73], v[72:73], v[2:3] op_sel_hi:[1,0]
	v_pk_mul_f32 v[74:75], v[74:75], v[2:3] op_sel_hi:[1,0]
	v_pk_mul_f32 v[72:73], v[72:73], v[104:105]
	v_pk_mul_f32 v[74:75], v[74:75], v[106:107]
	global_store_dwordx4 v0, v[72:75], s[12:13] offset:-2048 nt
	v_pk_mul_f32 v[76:77], v[76:77], v[2:3] op_sel_hi:[1,0]
	v_pk_mul_f32 v[78:79], v[78:79], v[2:3] op_sel_hi:[1,0]
	v_pk_mul_f32 v[76:77], v[76:77], v[108:109]
	v_pk_mul_f32 v[78:79], v[78:79], v[110:111]
	global_store_dwordx4 v0, v[76:79], s[12:13] offset:-1024 nt
	v_pk_mul_f32 v[80:81], v[80:81], v[2:3] op_sel_hi:[1,0]
	v_pk_mul_f32 v[82:83], v[82:83], v[2:3] op_sel_hi:[1,0]
	v_pk_mul_f32 v[80:81], v[80:81], v[112:113]
	v_pk_mul_f32 v[82:83], v[82:83], v[114:115]
	global_store_dwordx4 v0, v[80:83], s[12:13] offset:0 nt
	v_pk_mul_f32 v[84:85], v[84:85], v[2:3] op_sel_hi:[1,0]
	v_pk_mul_f32 v[86:87], v[86:87], v[2:3] op_sel_hi:[1,0]
	v_pk_mul_f32 v[84:85], v[84:85], v[116:117]
	v_pk_mul_f32 v[86:87], v[86:87], v[118:119]
	global_store_dwordx4 v0, v[84:87], s[12:13] offset:1024 nt
	v_pk_mul_f32 v[88:89], v[88:89], v[2:3] op_sel_hi:[1,0]
	v_pk_mul_f32 v[90:91], v[90:91], v[2:3] op_sel_hi:[1,0]
	v_pk_mul_f32 v[88:89], v[88:89], v[120:121]
	v_pk_mul_f32 v[90:91], v[90:91], v[122:123]
	global_store_dwordx4 v0, v[88:91], s[12:13] offset:2048 nt
	v_pk_mul_f32 v[92:93], v[92:93], v[2:3] op_sel_hi:[1,0]
	v_pk_mul_f32 v[94:95], v[94:95], v[2:3] op_sel_hi:[1,0]
	v_pk_mul_f32 v[92:93], v[92:93], v[124:125]
	v_pk_mul_f32 v[94:95], v[94:95], v[126:127]
	global_store_dwordx4 v0, v[92:95], s[12:13] offset:3072 nt
	s_mov_b64 s[12:13], s[8:9]
	s_mov_b32 s3, 1
	s_cmp_eq_u32 s0, 0
	s_cbranch_scc1 .LBB0_841
	s_branch .Lp8r_loop
